# residual-epilogue GEMM loop: last derived LDS-DMA group in saddr form with vcc as a third spare SGPR pair (4 more VALU 64-bit adds removed, 1 left)
# baseline (speedup 1.0000x reference)
; #define PG8_STAGE(bufoff, gbase, voff) do { _Pragma("unroll") for (int _i = 0; _i < 2; ++_i) \
;         __builtin_amdgcn_global_load_lds((const unsigned*)((const char*)(gbase) + (voff)[_i]), (LAS unsigned*)(lds + (bufoff) + ldsw + _i * 8192), 16, 0, 0); } while (0)
; #define PG8_LDA(dst, b, h) do { _Pragma("unroll") for (int m = 0; m < 4; ++m) _Pragma("unroll") for (int k = 0; k < 2; ++k) dst[m][k] = *(const LAS bf16x8*)(lds + PG8_SA(b, h) + aoff + m * 2048 + k * 1024); } while (0)
; #define PG8_LDB(dst, b, h) do { _Pragma("unroll") for (int n = 0; n < 2; ++n) _Pragma("unroll") for (int k = 0; k < 2; ++k) dst[n][k] = *(const LAS bf16x8*)(lds + PG8_SB(b, h) + boff + n * 2048 + k * 1024); } while (0)
; #define PG8_MMA(ai, bj, At, Bt) do { __builtin_amdgcn_s_setprio(1); _Pragma("unroll") for (int m = 0; m < 4; ++m) _Pragma("unroll") for (int n = 0; n < 2; ++n) _Pragma("unroll") for (int k = 0; k < 2; ++k) \
;         acc[ai][bj][m][n] = __builtin_amdgcn_mfma_f32_16x16x32_bf16(Bt[n][k], At[m][k], acc[ai][bj][m][n], 0, 0, 0); __builtin_amdgcn_s_setprio(0); } while (0)
; #define PG8_WAIT_V(n) asm volatile("s_waitcnt vmcnt(" #n ")" ::: "memory")
; #define PG8_WAIT_L(n) asm volatile("s_waitcnt lgkmcnt(" #n ")" ::: "memory")
; #define PG8_BAR __builtin_amdgcn_s_barrier()
; template <class Epi>
; __device__ __forceinline__ void gemm_phase(LAS unsigned char* lds, const Gemm g, const StaticOrder& S, const Epi& E) {
;     ...
;             const bool last = (t == nt - 2);
;             const char* a1 = cA + (size_t)(t + 1) * kstep;
;             const char* a2 = last ? nA : cA + (size_t)(t + 2) * kstep; const char* b2 = last ? nB : cB + (size_t)(t + 2) * kstep;
;             const char* a3 = a2 + kstep; const char* b3 = b2 + kstep;
;             PG8_LDB(B0, 0, 0); PG8_SCHED; PG8_LDA(At, 0, 0); PG8_STAGE(PG8_SA(1, 1), a1 + hstep, voffA);
;             PG8_WAIT_L(8); PG8_BAR; PG8_WAIT_L(0); PG8_MMA(0, 0, At, B0); PG8_BAR; PG8_SCHED;
;             PG8_LDB(B1, 0, 1); PG8_STAGE(PG8_SB(0, 0), b2, voffB);
;             PG8_BAR; PG8_WAIT_L(0); PG8_MMA(0, 1, At, B1); PG8_BAR;
;             PG8_LDA(At, 0, 1); PG8_STAGE(PG8_SA(0, 0), a2, voffA);
;             PG8_BAR; PG8_WAIT_L(0); PG8_MMA(1, 0, At, B0); PG8_BAR; PG8_SCHED;
;             PG8_STAGE(PG8_SB(0, 1), b2 + hstep, voffB);
;             PG8_WAIT_V(6); PG8_BAR; PG8_MMA(1, 1, At, B1); PG8_BAR;
.LBB0_591:
	s_add_i32 s68, s8, 2
	s_add_u32 s36, s0, 0x80
	s_addc_u32 s9, s1, 0
	s_add_i32 s66, 0, 0x10000
	ds_read_b128 v[48:51], v233
	ds_read_b128 v[52:55], v233 offset:1024
	ds_read_b128 v[56:59], v233 offset:2048
	ds_read_b128 v[60:63], v233 offset:3072
	s_cmp_eq_u32 s55, s8
	s_cselect_b32 s8, s34, s36
	s_cselect_b32 s9, s35, s9
	s_cselect_b32 s37, s11, s63
	s_cselect_b32 s36, s10, s43
	s_add_i32 m0, s44, 0xc000
	ds_read_b128 v[68:71], v248
	ds_read_b128 v[76:79], v248 offset:1024
	ds_read_b128 v[80:83], v248 offset:2048
	ds_read_b128 v[84:87], v248 offset:3072
	ds_read_b128 v[160:163], v248 offset:4096
	ds_read_b128 v[164:167], v248 offset:5120
	ds_read_b128 v[168:171], v248 offset:6144
	ds_read_b128 v[172:175], v248 offset:7168
	global_load_lds_dwordx4 v214, s[0:1]
	s_add_i32 m0, s44, 0xe000
	s_nop 0
	global_load_lds_dwordx4 v216, s[0:1]
	s_waitcnt lgkmcnt(8)
	s_barrier
	s_waitcnt lgkmcnt(0)
	v_mfma_f32_16x16x32_bf16 v[156:159], v[48:51], v[68:71], v[156:159]
	v_mfma_f32_16x16x32_bf16 v[156:159], v[52:55], v[76:79], v[156:159]
	v_mfma_f32_16x16x32_bf16 v[140:143], v[48:51], v[80:83], v[140:143]
	v_mfma_f32_16x16x32_bf16 v[140:143], v[52:55], v[84:87], v[140:143]
	v_mfma_f32_16x16x32_bf16 v[124:127], v[48:51], v[160:163], v[124:127]
	v_mfma_f32_16x16x32_bf16 v[124:127], v[52:55], v[164:167], v[124:127]
	v_mfma_f32_16x16x32_bf16 v[108:111], v[48:51], v[168:171], v[108:111]
	v_mfma_f32_16x16x32_bf16 v[108:111], v[52:55], v[172:175], v[108:111]
	v_mfma_f32_16x16x32_bf16 v[104:107], v[56:59], v[168:171], v[104:107]
	v_mfma_f32_16x16x32_bf16 v[104:107], v[60:63], v[172:175], v[104:107]
	v_mfma_f32_16x16x32_bf16 v[120:123], v[56:59], v[160:163], v[120:123]
	v_mfma_f32_16x16x32_bf16 v[120:123], v[60:63], v[164:167], v[120:123]
	v_mfma_f32_16x16x32_bf16 v[136:139], v[56:59], v[80:83], v[136:139]
	v_mfma_f32_16x16x32_bf16 v[136:139], v[60:63], v[84:87], v[136:139]
	v_mfma_f32_16x16x32_bf16 v[152:155], v[56:59], v[68:71], v[152:155]
	v_mfma_f32_16x16x32_bf16 v[152:155], v[60:63], v[76:79], v[152:155]
	s_barrier
	s_add_i32 s67, 0, 0x14000
	s_add_i32 s66, s66, s41
	s_mov_b32 m0, s66
	ds_read_b128 v[176:179], v233 offset:16384
	ds_read_b128 v[180:183], v233 offset:17408
	ds_read_b128 v[218:221], v233 offset:18432
	ds_read_b128 v[222:225], v233 offset:19456
	global_load_lds_dwordx4 v184, s[36:37]
	s_add_u32 s98, s36, s58
	s_addc_u32 s99, s37, s59
	s_add_i32 m0, s66, 0x2000
	s_nop 0
	global_load_lds_dwordx4 v212, s[36:37]
	s_barrier
	s_waitcnt lgkmcnt(0)
	v_mfma_f32_16x16x32_bf16 v[148:151], v[176:179], v[68:71], v[148:151]
	v_mfma_f32_16x16x32_bf16 v[68:71], v[218:221], v[68:71], v[144:147]
	v_mfma_f32_16x16x32_bf16 v[148:151], v[180:183], v[76:79], v[148:151]
	v_mfma_f32_16x16x32_bf16 v[68:71], v[222:225], v[76:79], v[68:71]
	v_mfma_f32_16x16x32_bf16 v[76:79], v[176:179], v[80:83], v[132:135]
	v_mfma_f32_16x16x32_bf16 v[80:83], v[218:221], v[80:83], v[128:131]
	v_mfma_f32_16x16x32_bf16 v[112:115], v[218:221], v[160:163], v[112:115]
	v_mfma_f32_16x16x32_bf16 v[100:103], v[176:179], v[168:171], v[100:103]
	v_mfma_f32_16x16x32_bf16 v[96:99], v[218:221], v[168:171], v[96:99]
	v_mfma_f32_16x16x32_bf16 v[76:79], v[180:183], v[84:87], v[76:79]
	v_mfma_f32_16x16x32_bf16 v[80:83], v[222:225], v[84:87], v[80:83]
	v_mfma_f32_16x16x32_bf16 v[84:87], v[176:179], v[160:163], v[116:119]
	v_mfma_f32_16x16x32_bf16 v[112:115], v[222:225], v[164:167], v[112:115]
	v_mfma_f32_16x16x32_bf16 v[100:103], v[180:183], v[172:175], v[100:103]
	v_mfma_f32_16x16x32_bf16 v[96:99], v[222:225], v[172:175], v[96:99]
	v_mfma_f32_16x16x32_bf16 v[84:87], v[180:183], v[164:167], v[84:87]
	s_mov_b32 m0, s44
	s_barrier
	ds_read_b128 v[116:119], v248 offset:16384
	ds_read_b128 v[128:131], v248 offset:17408
	ds_read_b128 v[132:135], v248 offset:18432
	ds_read_b128 v[144:147], v248 offset:19456
	ds_read_b128 v[160:163], v248 offset:20480
	ds_read_b128 v[164:167], v248 offset:21504
	ds_read_b128 v[168:171], v248 offset:22528
	ds_read_b128 v[172:175], v248 offset:23552
	global_load_lds_dwordx4 v208, s[8:9]
	s_add_u32 s100, s8, s58
	s_addc_u32 s101, s9, s59
	s_mov_b32 m0, s45
	s_nop 0
	global_load_lds_dwordx4 v210, s[8:9]
	s_barrier
	s_waitcnt lgkmcnt(0)
	v_mfma_f32_16x16x32_bf16 v[92:95], v[48:51], v[116:119], v[92:95]
	v_mfma_f32_16x16x32_bf16 v[92:95], v[52:55], v[128:131], v[92:95]
	v_mfma_f32_16x16x32_bf16 v[44:47], v[48:51], v[132:135], v[44:47]
	v_mfma_f32_16x16x32_bf16 v[44:47], v[52:55], v[144:147], v[44:47]
	v_mfma_f32_16x16x32_bf16 v[28:31], v[48:51], v[160:163], v[28:31]
	v_mfma_f32_16x16x32_bf16 v[28:31], v[52:55], v[164:167], v[28:31]
	v_mfma_f32_16x16x32_bf16 v[12:15], v[48:51], v[168:171], v[12:15]
	v_mfma_f32_16x16x32_bf16 v[12:15], v[52:55], v[172:175], v[12:15]
	v_mfma_f32_16x16x32_bf16 v[8:11], v[56:59], v[168:171], v[8:11]
	v_mfma_f32_16x16x32_bf16 v[8:11], v[60:63], v[172:175], v[8:11]
	v_mfma_f32_16x16x32_bf16 v[24:27], v[56:59], v[160:163], v[24:27]
	v_mfma_f32_16x16x32_bf16 v[24:27], v[60:63], v[164:167], v[24:27]
	v_mfma_f32_16x16x32_bf16 v[40:43], v[56:59], v[132:135], v[40:43]
	v_mfma_f32_16x16x32_bf16 v[40:43], v[60:63], v[144:147], v[40:43]
	v_mfma_f32_16x16x32_bf16 v[88:91], v[56:59], v[116:119], v[88:91]
	v_mfma_f32_16x16x32_bf16 v[88:91], v[60:63], v[128:131], v[88:91]
	s_barrier
	s_add_u32 s36, s36, s52
	s_addc_u32 s37, s37, 0
	s_add_i32 s66, s67, s41
	s_mov_b32 m0, s66
	s_add_u32 vcc_lo, s36, s58
	s_addc_u32 vcc_hi, s37, s59
	global_load_lds_dwordx4 v184, s[36:37]
	s_add_i32 m0, s66, 0x2000
	s_nop 0
	global_load_lds_dwordx4 v212, s[36:37]
	s_waitcnt vmcnt(6)
	s_barrier
; #define PG8_STAGE(bufoff, gbase, voff) do { _Pragma("unroll") for (int _i = 0; _i < 2; ++_i) \
;         __builtin_amdgcn_global_load_lds((const unsigned*)((const char*)(gbase) + (voff)[_i]), (LAS unsigned*)(lds + (bufoff) + ldsw + _i * 8192), 16, 0, 0); } while (0)
; #define PG8_LDA(dst, b, h) do { _Pragma("unroll") for (int m = 0; m < 4; ++m) _Pragma("unroll") for (int k = 0; k < 2; ++k) dst[m][k] = *(const LAS bf16x8*)(lds + PG8_SA(b, h) + aoff + m * 2048 + k * 1024); } while (0)
; #define PG8_LDB(dst, b, h) do { _Pragma("unroll") for (int n = 0; n < 2; ++n) _Pragma("unroll") for (int k = 0; k < 2; ++k) dst[n][k] = *(const LAS bf16x8*)(lds + PG8_SB(b, h) + boff + n * 2048 + k * 1024); } while (0)
; #define PG8_MMA(ai, bj, At, Bt) do { __builtin_amdgcn_s_setprio(1); _Pragma("unroll") for (int m = 0; m < 4; ++m) _Pragma("unroll") for (int n = 0; n < 2; ++n) _Pragma("unroll") for (int k = 0; k < 2; ++k) \
;         acc[ai][bj][m][n] = __builtin_amdgcn_mfma_f32_16x16x32_bf16(Bt[n][k], At[m][k], acc[ai][bj][m][n], 0, 0, 0); __builtin_amdgcn_s_setprio(0); } while (0)
; #define PG8_WAIT_V(n) asm volatile("s_waitcnt vmcnt(" #n ")" ::: "memory")
; #define PG8_WAIT_L(n) asm volatile("s_waitcnt lgkmcnt(" #n ")" ::: "memory")
; #define PG8_BAR __builtin_amdgcn_s_barrier()
; #define PG8_SCHED __builtin_amdgcn_sched_barrier(0)
; template <class Epi>
; __device__ __forceinline__ void gemm_phase(LAS unsigned char* lds, const Gemm g, const StaticOrder& S, const Epi& E) {
;     ...
;             PG8_WAIT_V(6); PG8_BAR; PG8_MMA(1, 1, At, B1); PG8_BAR;
;             PG8_LDB(B0, 1, 0); PG8_SCHED; PG8_LDA(At, 1, 0); PG8_STAGE(PG8_SA(0, 1), a2 + hstep, voffA);
;             PG8_WAIT_L(8); PG8_BAR; PG8_WAIT_L(0); PG8_MMA(0, 0, At, B0); PG8_BAR; PG8_SCHED;
;             PG8_LDB(B1, 1, 1); PG8_STAGE(PG8_SB(1, 0), b3, voffB);
;             PG8_BAR; PG8_WAIT_L(0); PG8_MMA(0, 1, At, B1); PG8_BAR;
	v_mfma_f32_16x16x32_bf16 v[36:39], v[176:179], v[132:135], v[36:39]
	v_mfma_f32_16x16x32_bf16 v[36:39], v[180:183], v[144:147], v[36:39]
	v_mfma_f32_16x16x32_bf16 v[20:23], v[176:179], v[160:163], v[20:23]
	v_mfma_f32_16x16x32_bf16 v[20:23], v[180:183], v[164:167], v[20:23]
	v_mfma_f32_16x16x32_bf16 v[4:7], v[176:179], v[168:171], v[4:7]
	v_mfma_f32_16x16x32_bf16 v[4:7], v[180:183], v[172:175], v[4:7]
	v_mfma_f32_16x16x32_bf16 v[48:51], v[176:179], v[116:119], v[72:75]
	v_mfma_f32_16x16x32_bf16 v[48:51], v[180:183], v[128:131], v[48:51]
	v_mfma_f32_16x16x32_bf16 v[52:55], v[218:221], v[116:119], v[64:67]
	v_mfma_f32_16x16x32_bf16 v[52:55], v[222:225], v[128:131], v[52:55]
	v_mfma_f32_16x16x32_bf16 v[0:3], v[218:221], v[168:171], v[0:3]
	v_mfma_f32_16x16x32_bf16 v[0:3], v[222:225], v[172:175], v[0:3]
	v_mfma_f32_16x16x32_bf16 v[16:19], v[218:221], v[160:163], v[16:19]
	v_mfma_f32_16x16x32_bf16 v[16:19], v[222:225], v[164:167], v[16:19]
	v_mfma_f32_16x16x32_bf16 v[32:35], v[218:221], v[132:135], v[32:35]
	v_mfma_f32_16x16x32_bf16 v[32:35], v[222:225], v[144:147], v[32:35]
	s_add_i32 s36, 0, 0x18000
	s_barrier
	ds_read_b128 v[56:59], v233 offset:32768
	ds_read_b128 v[60:63], v233 offset:33792
	ds_read_b128 v[64:67], v233 offset:34816
	ds_read_b128 v[72:75], v233 offset:35840
	s_add_u32 s8, s8, s52
	s_addc_u32 s9, s9, 0
	s_mov_b32 m0, s46
	ds_read_b128 v[116:119], v248 offset:32768
	ds_read_b128 v[128:131], v248 offset:33792
	ds_read_b128 v[160:163], v248 offset:34816
	ds_read_b128 v[164:167], v248 offset:35840
	ds_read_b128 v[168:171], v248 offset:36864
	ds_read_b128 v[172:175], v248 offset:37888
	ds_read_b128 v[176:179], v248 offset:38912
	ds_read_b128 v[180:183], v248 offset:39936
	global_load_lds_dwordx4 v208, s[8:9]
	v_lshl_add_u64 v[132:133], s[8:9], 0, v[210:211]
	s_mov_b32 m0, s47
	s_nop 0
	global_load_lds_dwordx4 v[132:133], off
	s_waitcnt lgkmcnt(8)
	s_barrier
	s_waitcnt lgkmcnt(0)
	v_mfma_f32_16x16x32_bf16 v[132:135], v[56:59], v[116:119], v[156:159]
	v_mfma_f32_16x16x32_bf16 v[156:159], v[60:63], v[128:131], v[132:135]
	v_mfma_f32_16x16x32_bf16 v[132:135], v[64:67], v[116:119], v[152:155]
	v_mfma_f32_16x16x32_bf16 v[152:155], v[72:75], v[128:131], v[132:135]
	v_mfma_f32_16x16x32_bf16 v[132:135], v[56:59], v[160:163], v[140:143]
	v_mfma_f32_16x16x32_bf16 v[140:143], v[60:63], v[164:167], v[132:135]
	v_mfma_f32_16x16x32_bf16 v[132:135], v[64:67], v[160:163], v[136:139]
	v_mfma_f32_16x16x32_bf16 v[124:127], v[56:59], v[168:171], v[124:127]
	v_mfma_f32_16x16x32_bf16 v[120:123], v[64:67], v[168:171], v[120:123]
	v_mfma_f32_16x16x32_bf16 v[108:111], v[56:59], v[176:179], v[108:111]
	v_mfma_f32_16x16x32_bf16 v[104:107], v[64:67], v[176:179], v[104:107]
	v_mfma_f32_16x16x32_bf16 v[136:139], v[72:75], v[164:167], v[132:135]
	v_mfma_f32_16x16x32_bf16 v[124:127], v[60:63], v[172:175], v[124:127]
	v_mfma_f32_16x16x32_bf16 v[120:123], v[72:75], v[172:175], v[120:123]
	v_mfma_f32_16x16x32_bf16 v[108:111], v[60:63], v[180:183], v[108:111]
	v_mfma_f32_16x16x32_bf16 v[104:107], v[72:75], v[180:183], v[104:107]
	s_barrier
	s_add_i32 s8, 0, 0x1c000
	s_add_i32 s9, s36, s41
	ds_read_b128 v[218:221], v233 offset:49152
	ds_read_b128 v[222:225], v233 offset:50176
	ds_read_b128 v[226:229], v233 offset:51200
	ds_read_b128 v[204:207], v233 offset:52224
	s_mov_b32 m0, s9
	s_nop 0
	global_load_lds_dwordx4 v184, s[98:99]
	s_add_i32 m0, s9, 0x2000
	s_nop 0
	global_load_lds_dwordx4 v212, s[98:99]
	s_barrier
	s_waitcnt lgkmcnt(0)
	v_mfma_f32_16x16x32_bf16 v[68:71], v[226:229], v[116:119], v[68:71]
	v_mfma_f32_16x16x32_bf16 v[132:135], v[218:221], v[116:119], v[148:151]
	v_mfma_f32_16x16x32_bf16 v[144:147], v[204:207], v[128:131], v[68:71]
	v_mfma_f32_16x16x32_bf16 v[68:71], v[218:221], v[160:163], v[76:79]
	v_mfma_f32_16x16x32_bf16 v[148:151], v[222:225], v[128:131], v[132:135]
	v_mfma_f32_16x16x32_bf16 v[132:135], v[222:225], v[164:167], v[68:71]
	v_mfma_f32_16x16x32_bf16 v[68:71], v[226:229], v[160:163], v[80:83]
	v_mfma_f32_16x16x32_bf16 v[128:131], v[204:207], v[164:167], v[68:71]
	v_mfma_f32_16x16x32_bf16 v[68:71], v[218:221], v[168:171], v[84:87]
	v_mfma_f32_16x16x32_bf16 v[116:119], v[222:225], v[172:175], v[68:71]
	v_mfma_f32_16x16x32_bf16 v[68:71], v[226:229], v[168:171], v[112:115]
	v_mfma_f32_16x16x32_bf16 v[112:115], v[204:207], v[172:175], v[68:71]
	v_mfma_f32_16x16x32_bf16 v[68:71], v[218:221], v[176:179], v[100:103]
	v_mfma_f32_16x16x32_bf16 v[100:103], v[222:225], v[180:183], v[68:71]
	v_mfma_f32_16x16x32_bf16 v[68:71], v[226:229], v[176:179], v[96:99]
	v_mfma_f32_16x16x32_bf16 v[96:99], v[204:207], v[180:183], v[68:71]
	s_mov_b32 m0, s50
	s_barrier
; #define PG8_STAGE(bufoff, gbase, voff) do { _Pragma("unroll") for (int _i = 0; _i < 2; ++_i) \
;         __builtin_amdgcn_global_load_lds((const unsigned*)((const char*)(gbase) + (voff)[_i]), (LAS unsigned*)(lds + (bufoff) + ldsw + _i * 8192), 16, 0, 0); } while (0)
; #define PG8_LDA(dst, b, h) do { _Pragma("unroll") for (int m = 0; m < 4; ++m) _Pragma("unroll") for (int k = 0; k < 2; ++k) dst[m][k] = *(const LAS bf16x8*)(lds + PG8_SA(b, h) + aoff + m * 2048 + k * 1024); } while (0)
; #define PG8_MMA(ai, bj, At, Bt) do { __builtin_amdgcn_s_setprio(1); _Pragma("unroll") for (int m = 0; m < 4; ++m) _Pragma("unroll") for (int n = 0; n < 2; ++n) _Pragma("unroll") for (int k = 0; k < 2; ++k) \
;         acc[ai][bj][m][n] = __builtin_amdgcn_mfma_f32_16x16x32_bf16(Bt[n][k], At[m][k], acc[ai][bj][m][n], 0, 0, 0); __builtin_amdgcn_s_setprio(0); } while (0)
; #define PG8_WAIT_V(n) asm volatile("s_waitcnt vmcnt(" #n ")" ::: "memory")
; #define PG8_WAIT_L(n) asm volatile("s_waitcnt lgkmcnt(" #n ")" ::: "memory")
; #define PG8_BAR __builtin_amdgcn_s_barrier()
; #define PG8_SCHED __builtin_amdgcn_sched_barrier(0)
; template <class Epi>
; __device__ __forceinline__ void gemm_phase(LAS unsigned char* lds, const Gemm g, const StaticOrder& S, const Epi& E) {
;     ...
;             PG8_LDA(At, 1, 1); PG8_STAGE(PG8_SA(1, 0), a3, voffA);
;             PG8_BAR; PG8_WAIT_L(0); PG8_MMA(1, 0, At, B0); PG8_BAR; PG8_SCHED;
;             PG8_STAGE(PG8_SB(1, 1), b3 + hstep, voffB);
;             PG8_WAIT_V(6); PG8_BAR; PG8_MMA(1, 1, At, B1); PG8_BAR;
;     __device__ __forceinline__ void operator()(const Acc& acc, const Unit& u, int wr, int wc, int fr, int fq) const {
;     ...
;         if (stats) {
; #pragma unroll
;             for (int bj = 0; bj < 2; ++bj)
; #pragma unroll
;                 for (int n = 0; n < 2; ++n) { gv[bj][n] = *(const f32x4*)(lg + col0 + bj * 128 + n * 4); bv[bj][n] = *(const f32x4*)(lb + col0 + bj * 128 + n * 4); } }
	s_nop 2
	ds_read_b128 v[68:71], v248 offset:49152
	ds_read_b128 v[76:79], v248 offset:50176
	ds_read_b128 v[80:83], v248 offset:51200
	ds_read_b128 v[84:87], v248 offset:52224
	ds_read_b128 v[160:163], v248 offset:53248
	ds_read_b128 v[164:167], v248 offset:54272
	ds_read_b128 v[168:171], v248 offset:55296
	ds_read_b128 v[172:175], v248 offset:56320
	global_load_lds_dwordx4 v208, s[100:101]
	s_mov_b32 m0, s51
	s_nop 0
	global_load_lds_dwordx4 v210, s[100:101]
	s_barrier
	s_waitcnt lgkmcnt(0)
	v_mfma_f32_16x16x32_bf16 v[92:95], v[56:59], v[68:71], v[92:95]
	v_mfma_f32_16x16x32_bf16 v[92:95], v[60:63], v[76:79], v[92:95]
	v_mfma_f32_16x16x32_bf16 v[44:47], v[56:59], v[80:83], v[44:47]
	v_mfma_f32_16x16x32_bf16 v[44:47], v[60:63], v[84:87], v[44:47]
	v_mfma_f32_16x16x32_bf16 v[28:31], v[56:59], v[160:163], v[28:31]
	v_mfma_f32_16x16x32_bf16 v[28:31], v[60:63], v[164:167], v[28:31]
	v_mfma_f32_16x16x32_bf16 v[12:15], v[56:59], v[168:171], v[12:15]
	v_mfma_f32_16x16x32_bf16 v[12:15], v[60:63], v[172:175], v[12:15]
	v_mfma_f32_16x16x32_bf16 v[8:11], v[64:67], v[168:171], v[8:11]
	v_mfma_f32_16x16x32_bf16 v[8:11], v[72:75], v[172:175], v[8:11]
	v_mfma_f32_16x16x32_bf16 v[24:27], v[64:67], v[160:163], v[24:27]
	v_mfma_f32_16x16x32_bf16 v[24:27], v[72:75], v[164:167], v[24:27]
	v_mfma_f32_16x16x32_bf16 v[40:43], v[64:67], v[80:83], v[40:43]
	v_mfma_f32_16x16x32_bf16 v[40:43], v[72:75], v[84:87], v[40:43]
	v_mfma_f32_16x16x32_bf16 v[88:91], v[64:67], v[68:71], v[88:91]
	v_mfma_f32_16x16x32_bf16 v[88:91], v[72:75], v[76:79], v[88:91]
	s_barrier
	s_add_i32 s8, s8, s41
	s_mov_b32 m0, s8
	s_nop 0
	global_load_lds_dwordx4 v184, vcc
	s_add_i32 m0, s8, 0x2000
	s_nop 0
	global_load_lds_dwordx4 v212, vcc
	s_waitcnt vmcnt(6)
	s_barrier
	v_mfma_f32_16x16x32_bf16 v[48:51], v[218:221], v[68:71], v[48:51]
	v_mfma_f32_16x16x32_bf16 v[72:75], v[222:225], v[76:79], v[48:51]
	v_mfma_f32_16x16x32_bf16 v[48:51], v[226:229], v[68:71], v[52:55]
	v_mfma_f32_16x16x32_bf16 v[36:39], v[218:221], v[80:83], v[36:39]
	v_mfma_f32_16x16x32_bf16 v[32:35], v[226:229], v[80:83], v[32:35]
	v_mfma_f32_16x16x32_bf16 v[20:23], v[218:221], v[160:163], v[20:23]
	v_mfma_f32_16x16x32_bf16 v[16:19], v[226:229], v[160:163], v[16:19]
	v_mfma_f32_16x16x32_bf16 v[4:7], v[218:221], v[168:171], v[4:7]
	v_mfma_f32_16x16x32_bf16 v[0:3], v[226:229], v[168:171], v[0:3]
	v_mfma_f32_16x16x32_bf16 v[64:67], v[204:207], v[76:79], v[48:51]
	v_mfma_f32_16x16x32_bf16 v[36:39], v[222:225], v[84:87], v[36:39]
	v_mfma_f32_16x16x32_bf16 v[32:35], v[204:207], v[84:87], v[32:35]
	v_mfma_f32_16x16x32_bf16 v[20:23], v[222:225], v[164:167], v[20:23]
	v_mfma_f32_16x16x32_bf16 v[16:19], v[204:207], v[164:167], v[16:19]
	v_mfma_f32_16x16x32_bf16 v[4:7], v[222:225], v[172:175], v[4:7]
	v_mfma_f32_16x16x32_bf16 v[0:3], v[204:207], v[172:175], v[0:3]
	s_add_u32 s0, s0, 0x100
	s_addc_u32 s1, s1, 0
	s_add_u32 s43, s43, 0x100
	s_addc_u32 s63, s63, 0
	s_cmp_ge_u32 s68, s54
	s_mov_b32 s8, s68
	s_barrier
	s_cbranch_scc0 .LBB0_591
	v_lshl_or_b32 v224, s42, 8, v247
	v_cndmask_b32_e64 v48, 0, 1, s[30:31]
	v_cmp_ne_u32_e64 s[8:9], 1, v48
	s_andn2_b64 vcc, exec, s[30:31]
	v_ashrrev_i32_e32 v225, 31, v224
	s_cbranch_vccnz .LBB0_594
	v_lshlrev_b64 v[48:49], 2, v[224:225]
	v_lshl_add_u64 v[52:53], s[20:21], 0, v[48:49]
	v_lshl_add_u64 v[60:61], s[22:23], 0, v[48:49]
	global_load_dwordx4 v[68:71], v[52:53], off offset:16
	global_load_dwordx4 v[80:83], v[52:53], off
	global_load_dwordx4 v[76:79], v[60:61], off offset:16
	global_load_dwordx4 v[84:87], v[60:61], off
	global_load_dwordx4 v[48:51], v[52:53], off offset:528
	global_load_dwordx4 v[56:59], v[52:53], off offset:512
	s_nop 0
	global_load_dwordx4 v[52:55], v[60:61], off offset:528
	s_nop 0
	global_load_dwordx4 v[60:63], v[60:61], off offset:512
